# grid barrier: waiting workgroups poll the cross-XCC release generation directly (no per-XCC relay hop)
# speedup vs baseline: 1.0138x; 1.0027x over previous
.LBB0_47:
	s_or_b64 exec, exec, s[6:7]
	v_cvt_f32_u32_e32 v6, v4
	s_waitcnt vmcnt(0)
	v_readfirstlane_b32 s4, v5
	v_sub_u32_e32 v5, 0, v4
	v_rcp_iflag_f32_e32 v6, v6
	v_add_u32_e32 v7, s4, v3
	v_mul_f32_e32 v6, 0x4f7ffffe, v6
	v_cvt_u32_f32_e32 v6, v6
	v_mul_lo_u32 v3, v5, v6
	v_mul_hi_u32 v3, v6, v3
	v_add_u32_e32 v3, v6, v3
	v_mul_hi_u32 v3, v7, v3
	v_mul_lo_u32 v5, v3, v4
	v_sub_u32_e32 v5, v7, v5
	v_add_u32_e32 v6, 1, v3
	v_cmp_ge_u32_e32 vcc, v5, v4
	s_nop 1
	v_cndmask_b32_e32 v3, v3, v6, vcc
	v_sub_u32_e32 v6, v5, v4
	v_cndmask_b32_e32 v5, v5, v6, vcc
	v_add_u32_e32 v6, 1, v3
	v_cmp_ge_u32_e32 vcc, v5, v4
	v_add_u32_e32 v5, 1, v7
	s_nop 0
	v_cndmask_b32_e32 v3, v3, v6, vcc
	v_mul_lo_u32 v6, v4, v3
	v_add_u32_e32 v4, v6, v4
	v_cmp_ne_u32_e32 vcc, v5, v4
	s_and_saveexec_b64 s[4:5], vcc
	s_xor_b64 s[4:5], exec, s[4:5]
	s_cbranch_execz .LBB0_61
	s_waitcnt lgkmcnt(0)
	v_mov_b32_e32 v2, 0x7000
	buffer_inv sc1
	global_load_dword v2, v2, s[82:83] offset:1280 sc1
	s_add_u32 s12, s82, 0x7500
	s_addc_u32 s13, s83, 0
	s_waitcnt vmcnt(0)
	v_cmp_eq_u32_e32 vcc, v2, v3
	s_and_saveexec_b64 s[6:7], vcc
	s_cbranch_execz .LBB0_60
	s_add_u32 s8, s82, 0x4200
	s_addc_u32 s9, s83, 0
	s_mov_b32 s24, 1
	s_mov_b64 s[14:15], 0
	v_mov_b32_e32 v2, 0
	s_branch .LBB0_51

.LBB0_189:
	s_or_b64 exec, exec, s[6:7]
	v_cvt_f32_u32_e32 v6, v4
	s_waitcnt vmcnt(0)
	v_readfirstlane_b32 s4, v5
	v_sub_u32_e32 v5, 0, v4
	v_rcp_iflag_f32_e32 v6, v6
	v_add_u32_e32 v7, s4, v3
	v_mul_f32_e32 v6, 0x4f7ffffe, v6
	v_cvt_u32_f32_e32 v6, v6
	v_mul_lo_u32 v3, v5, v6
	v_mul_hi_u32 v3, v6, v3
	v_add_u32_e32 v3, v6, v3
	v_mul_hi_u32 v3, v7, v3
	v_mul_lo_u32 v5, v3, v4
	v_sub_u32_e32 v5, v7, v5
	v_add_u32_e32 v6, 1, v3
	v_cmp_ge_u32_e32 vcc, v5, v4
	s_nop 1
	v_cndmask_b32_e32 v3, v3, v6, vcc
	v_sub_u32_e32 v6, v5, v4
	v_cndmask_b32_e32 v5, v5, v6, vcc
	v_add_u32_e32 v6, 1, v3
	v_cmp_ge_u32_e32 vcc, v5, v4
	v_add_u32_e32 v5, 1, v7
	s_nop 0
	v_cndmask_b32_e32 v3, v3, v6, vcc
	v_mul_lo_u32 v6, v4, v3
	v_add_u32_e32 v4, v6, v4
	v_cmp_ne_u32_e32 vcc, v5, v4
	s_and_saveexec_b64 s[4:5], vcc
	s_xor_b64 s[4:5], exec, s[4:5]
	s_cbranch_execz .LBB0_204
	s_waitcnt lgkmcnt(0)
	v_mov_b32_e32 v2, 0x7000
	buffer_inv sc1
	global_load_dword v2, v2, s[82:83] offset:1280 sc1
	s_add_u32 s10, s82, 0x7500
	s_addc_u32 s11, s83, 0
	s_waitcnt vmcnt(0)
	v_cmp_eq_u32_e32 vcc, v2, v3
	s_and_saveexec_b64 s[6:7], vcc
	s_cbranch_execz .LBB0_203
	s_add_u32 s8, s82, 0x4200
	s_addc_u32 s9, s83, 0
	s_mov_b32 s22, 1
	s_mov_b64 s[12:13], 0
	v_mov_b32_e32 v2, 0
	s_branch .LBB0_193

.LBB0_477:
	s_or_b64 exec, exec, s[8:9]
	v_cvt_f32_u32_e32 v6, v4
	s_waitcnt vmcnt(0)
	v_readfirstlane_b32 s6, v5
	v_sub_u32_e32 v5, 0, v4
	v_rcp_iflag_f32_e32 v6, v6
	v_add_u32_e32 v7, s6, v3
	v_mul_f32_e32 v6, 0x4f7ffffe, v6
	v_cvt_u32_f32_e32 v6, v6
	v_mul_lo_u32 v3, v5, v6
	v_mul_hi_u32 v3, v6, v3
	v_add_u32_e32 v3, v6, v3
	v_mul_hi_u32 v3, v7, v3
	v_mul_lo_u32 v5, v3, v4
	v_sub_u32_e32 v5, v7, v5
	v_add_u32_e32 v6, 1, v3
	v_cmp_ge_u32_e32 vcc, v5, v4
	s_nop 1
	v_cndmask_b32_e32 v3, v3, v6, vcc
	v_sub_u32_e32 v6, v5, v4
	v_cndmask_b32_e32 v5, v5, v6, vcc
	v_add_u32_e32 v6, 1, v3
	v_cmp_ge_u32_e32 vcc, v5, v4
	v_add_u32_e32 v5, 1, v7
	s_nop 0
	v_cndmask_b32_e32 v3, v3, v6, vcc
	v_mul_lo_u32 v6, v4, v3
	v_add_u32_e32 v4, v6, v4
	v_cmp_ne_u32_e32 vcc, v5, v4
	s_and_saveexec_b64 s[6:7], vcc
	s_xor_b64 s[6:7], exec, s[6:7]
	s_cbranch_execz .LBB0_491
	s_waitcnt lgkmcnt(0)
	v_mov_b32_e32 v2, 0x7000
	buffer_inv sc1
	global_load_dword v2, v2, s[82:83] offset:1280 sc1
	s_add_u32 s14, s82, 0x7500
	s_addc_u32 s15, s83, 0
	s_waitcnt vmcnt(0)
	v_cmp_eq_u32_e32 vcc, v2, v3
	s_and_saveexec_b64 s[8:9], vcc
	s_cbranch_execz .LBB0_490
	s_add_u32 s12, s82, 0x4200
	s_addc_u32 s13, s83, 0
	s_mov_b32 s26, 1
	s_mov_b64 s[16:17], 0
	v_mov_b32_e32 v2, 0
	s_branch .LBB0_481
